# grid barriers: non-leader workgroups poll the cross-XCC release word directly (no per-XCC relay hop) on top of v059
# baseline (speedup 1.0000x reference)
; __device__ __forceinline__ unsigned xb_ld(unsigned* p)              { return __hip_atomic_load(p, __ATOMIC_RELAXED, __HIP_MEMORY_SCOPE_AGENT); }
; __device__ __forceinline__ unsigned xb_add(unsigned* p, unsigned v) { return __hip_atomic_fetch_add(p, v, __ATOMIC_RELAXED, __HIP_MEMORY_SCOPE_AGENT); }
; #define XB_SPIN(cond, bar) do { unsigned _sp = 0; while (cond) { __builtin_amdgcn_s_sleep(1); \
;     if ((++_sp & 255u) == 0u) { if (xb_ld(&(bar)[XB_TMO])) break; if (_sp > XB_SPIN_CAP) { atomicAdd(&(bar)[XB_TMO], 1u); break; } } } } while (0)
; __device__ __forceinline__ void xcd_barrier(const XcdBarrier& b) {
;     ...
;         const unsigned old = xb_add(&bar[XB_XSUB(b.x)], 1u);
;         const unsigned gen = old / nloc;
;         if (old + 1u == (gen + 1u) * nloc) {
;             __builtin_amdgcn_fence(__ATOMIC_RELEASE, "agent");
;             asm volatile("s_waitcnt vmcnt(0)" ::: "memory");
;             const unsigned og = xb_add(&bar[XB_TOP], 1u);
;             const unsigned tg = og / nx;
;             if (og + 1u == (tg + 1u) * nx) xb_add(&bar[XB_TOPGEN], 1u);
;             else XB_SPIN(xb_ld(&bar[XB_TOPGEN]) == tg, bar);
;             __builtin_amdgcn_fence(__ATOMIC_ACQUIRE, "agent");
;             xb_add(&bar[XB_XGEN(b.x)], 1u);
;             asm volatile("s_waitcnt vmcnt(0)" ::: "memory");
;         } else {
;             XB_SPIN(xb_ld(&bar[XB_XGEN(b.x)]) == gen, bar);
.LBB0_130:
	s_or_b64 exec, exec, s[10:11]
	v_cvt_f32_u32_e32 v4, v2
	s_waitcnt vmcnt(0)
	v_readfirstlane_b32 s0, v3
	v_sub_u32_e32 v3, 0, v2
	v_rcp_iflag_f32_e32 v4, v4
	v_add_u32_e32 v5, s0, v1
	v_mul_f32_e32 v4, 0x4f7ffffe, v4
	v_cvt_u32_f32_e32 v4, v4
	v_mul_lo_u32 v1, v3, v4
	v_mul_hi_u32 v1, v4, v1
	v_add_u32_e32 v1, v4, v1
	v_mul_hi_u32 v1, v5, v1
	v_mul_lo_u32 v3, v1, v2
	v_sub_u32_e32 v3, v5, v3
	v_add_u32_e32 v4, 1, v1
	v_cmp_ge_u32_e32 vcc, v3, v2
	s_nop 1
	v_cndmask_b32_e32 v1, v1, v4, vcc
	v_sub_u32_e32 v4, v3, v2
	v_cndmask_b32_e32 v3, v3, v4, vcc
	v_add_u32_e32 v4, 1, v1
	v_cmp_ge_u32_e32 vcc, v3, v2
	v_add_u32_e32 v3, 1, v5
	s_nop 0
	v_cndmask_b32_e32 v1, v1, v4, vcc
	v_mul_lo_u32 v4, v2, v1
	v_add_u32_e32 v2, v4, v2
	v_cmp_ne_u32_e32 vcc, v3, v2
	s_and_saveexec_b64 s[0:1], vcc
	s_xor_b64 s[8:9], exec, s[0:1]
	s_cbranch_execz .LBB0_144
	s_waitcnt lgkmcnt(0)
	s_add_u32 s36, s28, 0x213500
	s_addc_u32 s37, s29, 0
	v_mov_b32_e32 v0, 0
	global_load_dword v0, v0, s[36:37] sc1
	s_waitcnt vmcnt(0)
	v_cmp_eq_u32_e32 vcc, v0, v1
	s_and_saveexec_b64 s[10:11], vcc
	s_cbranch_execz .LBB0_143
	s_add_u32 s12, s28, 0x210200
	s_addc_u32 s13, s29, 0
	s_mov_b32 s0, 1
	s_mov_b64 s[40:41], 0
	v_mov_b32_e32 v0, 0
	s_branch .LBB0_134

; __device__ __forceinline__ unsigned xb_ld(unsigned* p)              { return __hip_atomic_load(p, __ATOMIC_RELAXED, __HIP_MEMORY_SCOPE_AGENT); }
; __device__ __forceinline__ unsigned xb_add(unsigned* p, unsigned v) { return __hip_atomic_fetch_add(p, v, __ATOMIC_RELAXED, __HIP_MEMORY_SCOPE_AGENT); }
; #define XB_SPIN(cond, bar) do { unsigned _sp = 0; while (cond) { __builtin_amdgcn_s_sleep(1); \
;     if ((++_sp & 255u) == 0u) { if (xb_ld(&(bar)[XB_TMO])) break; if (_sp > XB_SPIN_CAP) { atomicAdd(&(bar)[XB_TMO], 1u); break; } } } } while (0)
; __device__ __forceinline__ void xcd_barrier(const XcdBarrier& b) {
;     ...
;         const unsigned old = xb_add(&bar[XB_XSUB(b.x)], 1u);
;         const unsigned gen = old / nloc;
;         if (old + 1u == (gen + 1u) * nloc) {
;             __builtin_amdgcn_fence(__ATOMIC_RELEASE, "agent");
;             asm volatile("s_waitcnt vmcnt(0)" ::: "memory");
;             const unsigned og = xb_add(&bar[XB_TOP], 1u);
;             const unsigned tg = og / nx;
;             if (og + 1u == (tg + 1u) * nx) xb_add(&bar[XB_TOPGEN], 1u);
;             else XB_SPIN(xb_ld(&bar[XB_TOPGEN]) == tg, bar);
;             __builtin_amdgcn_fence(__ATOMIC_ACQUIRE, "agent");
;             xb_add(&bar[XB_XGEN(b.x)], 1u);
;             asm volatile("s_waitcnt vmcnt(0)" ::: "memory");
;         } else {
;             XB_SPIN(xb_ld(&bar[XB_XGEN(b.x)]) == gen, bar);
.LBB0_519:
	s_or_b64 exec, exec, s[10:11]
	v_cvt_f32_u32_e32 v4, v2
	s_waitcnt vmcnt(0)
	v_readfirstlane_b32 s0, v3
	v_sub_u32_e32 v3, 0, v2
	v_rcp_iflag_f32_e32 v4, v4
	v_add_u32_e32 v5, s0, v1
	v_mul_f32_e32 v4, 0x4f7ffffe, v4
	v_cvt_u32_f32_e32 v4, v4
	v_mul_lo_u32 v1, v3, v4
	v_mul_hi_u32 v1, v4, v1
	v_add_u32_e32 v1, v4, v1
	v_mul_hi_u32 v1, v5, v1
	v_mul_lo_u32 v3, v1, v2
	v_sub_u32_e32 v3, v5, v3
	v_add_u32_e32 v4, 1, v1
	v_cmp_ge_u32_e32 vcc, v3, v2
	s_nop 1
	v_cndmask_b32_e32 v1, v1, v4, vcc
	v_sub_u32_e32 v4, v3, v2
	v_cndmask_b32_e32 v3, v3, v4, vcc
	v_add_u32_e32 v4, 1, v1
	v_cmp_ge_u32_e32 vcc, v3, v2
	v_add_u32_e32 v3, 1, v5
	s_nop 0
	v_cndmask_b32_e32 v1, v1, v4, vcc
	v_mul_lo_u32 v4, v2, v1
	v_add_u32_e32 v2, v4, v2
	v_cmp_ne_u32_e32 vcc, v3, v2
	s_and_saveexec_b64 s[0:1], vcc
	s_xor_b64 s[6:7], exec, s[0:1]
	s_cbranch_execz .LBB0_533
	s_waitcnt lgkmcnt(0)
	s_add_u32 s22, s28, 0x213500
	s_addc_u32 s23, s29, 0
	v_mov_b32_e32 v0, 0
	global_load_dword v0, v0, s[22:23] sc1
	s_waitcnt vmcnt(0)
	v_cmp_eq_u32_e32 vcc, v0, v1
	s_and_saveexec_b64 s[10:11], vcc
	s_cbranch_execz .LBB0_532
	s_add_u32 s20, s28, 0x210200
	s_addc_u32 s21, s29, 0
	s_mov_b32 s0, 1
	s_mov_b64 s[42:43], 0
	v_mov_b32_e32 v0, 0
	s_branch .LBB0_523

; __device__ __forceinline__ unsigned xb_ld(unsigned* p)              { return __hip_atomic_load(p, __ATOMIC_RELAXED, __HIP_MEMORY_SCOPE_AGENT); }
; __device__ __forceinline__ unsigned xb_add(unsigned* p, unsigned v) { return __hip_atomic_fetch_add(p, v, __ATOMIC_RELAXED, __HIP_MEMORY_SCOPE_AGENT); }
; #define XB_SPIN(cond, bar) do { unsigned _sp = 0; while (cond) { __builtin_amdgcn_s_sleep(1); \
;     if ((++_sp & 255u) == 0u) { if (xb_ld(&(bar)[XB_TMO])) break; if (_sp > XB_SPIN_CAP) { atomicAdd(&(bar)[XB_TMO], 1u); break; } } } } while (0)
; __device__ __forceinline__ void xcd_barrier(const XcdBarrier& b) {
;     ...
;         const unsigned old = xb_add(&bar[XB_XSUB(b.x)], 1u);
;         const unsigned gen = old / nloc;
;         if (old + 1u == (gen + 1u) * nloc) {
;             __builtin_amdgcn_fence(__ATOMIC_RELEASE, "agent");
;             asm volatile("s_waitcnt vmcnt(0)" ::: "memory");
;             const unsigned og = xb_add(&bar[XB_TOP], 1u);
;             const unsigned tg = og / nx;
;             if (og + 1u == (tg + 1u) * nx) xb_add(&bar[XB_TOPGEN], 1u);
;             else XB_SPIN(xb_ld(&bar[XB_TOPGEN]) == tg, bar);
;             __builtin_amdgcn_fence(__ATOMIC_ACQUIRE, "agent");
;             xb_add(&bar[XB_XGEN(b.x)], 1u);
;             asm volatile("s_waitcnt vmcnt(0)" ::: "memory");
;         } else {
;             XB_SPIN(xb_ld(&bar[XB_XGEN(b.x)]) == gen, bar);
.LBB0_680:
	s_or_b64 exec, exec, s[16:17]
	v_cvt_f32_u32_e32 v4, v2
	s_waitcnt vmcnt(0)
	v_readfirstlane_b32 s0, v3
	v_sub_u32_e32 v3, 0, v2
	v_rcp_iflag_f32_e32 v4, v4
	v_add_u32_e32 v5, s0, v1
	v_mul_f32_e32 v4, 0x4f7ffffe, v4
	v_cvt_u32_f32_e32 v4, v4
	v_mul_lo_u32 v1, v3, v4
	v_mul_hi_u32 v1, v4, v1
	v_add_u32_e32 v1, v4, v1
	v_mul_hi_u32 v1, v5, v1
	v_mul_lo_u32 v3, v1, v2
	v_sub_u32_e32 v3, v5, v3
	v_add_u32_e32 v4, 1, v1
	v_cmp_ge_u32_e32 vcc, v3, v2
	s_nop 1
	v_cndmask_b32_e32 v1, v1, v4, vcc
	v_sub_u32_e32 v4, v3, v2
	v_cndmask_b32_e32 v3, v3, v4, vcc
	v_add_u32_e32 v4, 1, v1
	v_cmp_ge_u32_e32 vcc, v3, v2
	v_add_u32_e32 v3, 1, v5
	s_nop 0
	v_cndmask_b32_e32 v1, v1, v4, vcc
	v_mul_lo_u32 v4, v2, v1
	v_add_u32_e32 v2, v4, v2
	v_cmp_ne_u32_e32 vcc, v3, v2
	s_and_saveexec_b64 s[0:1], vcc
	s_xor_b64 s[14:15], exec, s[0:1]
	s_cbranch_execz .LBB0_694
	s_waitcnt lgkmcnt(0)
	s_add_u32 s22, s28, 0x213500
	s_addc_u32 s23, s29, 0
	v_mov_b32_e32 v0, 0
	global_load_dword v0, v0, s[22:23] sc1
	s_waitcnt vmcnt(0)
	v_cmp_eq_u32_e32 vcc, v0, v1
	s_and_saveexec_b64 s[16:17], vcc
	s_cbranch_execz .LBB0_693
	s_add_u32 s18, s28, 0x210200
	s_addc_u32 s19, s29, 0
	s_mov_b32 s0, 1
	s_mov_b64 s[24:25], 0
	v_mov_b32_e32 v0, 0
	s_branch .LBB0_684
